# code placement: hot loop heads (attention key loop, both GEMM tile loops, both queue loops) aligned to 64 bytes
# speedup vs baseline: 1.0005x; 1.0005x over previous
.LBB0_184:
	s_bfe_u32 s0, s36, 0xf0001
	s_mul_i32 s0, s0, 0x89af
	s_lshr_b32 s0, s0, 22
	s_mul_i32 s1, s0, 0xee
	s_sub_i32 s1, s36, s1
	s_mul_i32 s4, s1, 37
	s_lshr_b32 s5, s4, 8
	s_sub_i32 s5, s1, s5
	s_bfe_u32 s5, s5, 0x70001
	s_bfe_u32 s4, s4, 0x80008
	s_add_i32 s5, s5, s4
	s_bfe_u32 s4, s5, 0x60002
	s_mul_i32 s5, s4, 7
	s_sub_i32 s1, s1, s5
	s_and_b32 s10, s1, 0xff
	s_mul_i32 s0, s0, 7
	s_add_i32 s10, s10, s0
	v_readlane_b32 s0, v252, 8
	s_lshl_b32 s22, s10, 7
	s_add_i32 s42, s0, s4
	s_lshl_b32 s0, s10, 18
	s_add_u32 s0, s66, s0
	s_addc_u32 s1, s67, 0
	s_lshl_b32 s4, s42, 18
	s_add_u32 s4, s20, s4
	s_addc_u32 s5, s21, 0
	v_add_u32_e32 v2, 0x30000, v172
	s_waitcnt vmcnt(16)
	.p2alignl 6, 3212836864

.LBB0_543:
	s_andn2_b64 vcc, exec, s[0:1]
	s_cbranch_vccz .LBB0_786
	.p2alignl 6, 3212836864

.LBB0_765:
	s_mul_i32 s0, s36, 0x1dc0000
	s_mul_hi_i32 s1, s36, 0x1dc0000
	s_add_u32 s0, s24, s0
	s_addc_u32 s1, s25, s1
	s_lshl_b32 s6, s4, 6
	s_and_b32 s33, s6, 0xc0
	s_lshl_b32 s22, s33, 1
	s_cmp_lt_u32 s5, 2
	v_mov_b32_e32 v18, v222
	s_cselect_b32 s38, 4, 0x44
	v_lshlrev_b32_e32 v0, 4, v18
	s_add_u32 s6, s0, s22
	v_and_b32_e32 v4, 0x70, v0
	v_mov_b32_e32 v5, v3
	s_addc_u32 s7, s1, 0
	v_lshl_add_u64 v[0:1], s[6:7], 0, v[4:5]
	s_mov_b64 s[6:7], 0x1600
	v_ashrrev_i32_e32 v19, 3, v18
	v_lshl_add_u64 v[6:7], v[0:1], 0, s[6:7]
	s_mov_b64 s[6:7], 0x1800
	v_lshl_add_u64 v[0:1], v[0:1], 0, s[6:7]
	v_add_u32_e32 v2, 32, v19
	v_mad_i64_i32 v[10:11], s[6:7], v19, s48, v[0:1]
	v_mad_i64_i32 v[12:13], s[6:7], v2, s48, v[0:1]
	v_ashrrev_i32_e32 v0, 1, v18
	v_and_b32_e32 v0, 0xffffffe0, v0
	v_and_b32_e32 v5, 31, v18
	v_lshl_add_u32 v0, s5, 7, v0
	v_or_b32_e32 v148, v0, v5
	v_mov_b64_e32 v[0:1], s[0:1]
	v_bfe_u32 v219, v18, 5, 1
	v_mad_i64_i32 v[0:1], s[0:1], v148, s48, v[0:1]
	v_mad_i64_i32 v[8:9], s[6:7], v19, s48, v[6:7]
	v_mad_i64_i32 v[6:7], s[6:7], v2, s48, v[6:7]
	v_lshl_add_u64 v[14:15], v[0:1], 0, s[22:23]
	v_lshlrev_b32_e32 v2, 4, v219
	v_lshl_add_u64 v[14:15], v[14:15], 0, v[2:3]
	s_mov_b64 s[0:1], 0x1400
	v_lshl_add_u64 v[16:17], v[14:15], 0, s[0:1]
	s_movk_i32 s0, 0x1000
	v_add_co_u32_e32 v14, vcc, s0, v14
	s_mov_b32 s0, 0x70000
	s_nop 0
	v_addc_co_u32_e32 v15, vcc, 0, v15, vcc
	global_load_dwordx4 v[100:103], v[8:9], off
	global_load_dwordx4 v[104:107], v[6:7], off
	v_add_co_u32_e32 v8, vcc, s0, v8
	global_load_dwordx4 v[112:115], v[10:11], off
	global_load_dwordx4 v[128:131], v[12:13], off
	v_addc_co_u32_e32 v9, vcc, 0, v9, vcc
	v_add_co_u32_e32 v6, vcc, s0, v6
	global_load_dwordx4 v[108:111], v[16:17], off offset:32
	global_load_dwordx4 v[116:119], v[16:17], off offset:64
	global_load_dwordx4 v[120:123], v[14:15], off offset:1024
	global_load_dwordx4 v[124:127], v[16:17], off offset:96
	v_addc_co_u32_e32 v7, vcc, 0, v7, vcc
	global_load_dwordx4 v[132:135], v[8:9], off
	global_load_dwordx4 v[136:139], v[6:7], off
	v_add_co_u32_e32 v6, vcc, s0, v10
	v_mul_u32_u24_e32 v5, 0x48, v5
	s_nop 0
	v_addc_co_u32_e32 v7, vcc, 0, v11, vcc
	v_add_co_u32_e32 v8, vcc, s0, v12
	s_movk_i32 s0, 0x90
	s_nop 0
	v_addc_co_u32_e32 v9, vcc, 0, v13, vcc
	global_load_dwordx4 v[140:143], v[6:7], off
	global_load_dwordx4 v[144:147], v[8:9], off
	v_lshrrev_b32_e32 v6, 3, v18
	v_bfe_u32 v7, v18, 2, 2
	v_mul_lo_u32 v9, v19, s0
	v_and_b32_e32 v8, 16, v18
	v_and_or_b32 v6, v6, 4, v7
	v_add3_u32 v239, 32, v9, v4
	v_lshlrev_b32_e32 v4, 2, v18
	v_lshlrev_b32_e32 v5, 1, v5
	v_and_or_b32 v4, v4, 12, v8
	v_add3_u32 v240, 32, v5, v2
	v_mul_u32_u24_e32 v5, 0x48, v6
	v_lshlrev_b32_e32 v4, 1, v4
	v_lshlrev_b32_e32 v5, 1, v5
	v_add3_u32 v241, 32, v4, v5
	v_add3_u32 v242, 32, v5, v4
	v_mad_i64_i32 v[4:5], s[0:1], v19, s48, 0
	v_mad_i64_i32 v[4:5], s[0:1], s36, v237, v[4:5]
	s_and_b32 s0, s4, 3
	v_and_b32_e32 v6, 7, v18
	s_lshl_b32 s0, s0, 7
	v_lshlrev_b32_e32 v6, 4, v6
	v_or3_b32 v4, v4, s0, v6
	v_mov_b32_e32 v18, v3
	v_mov_b32_e32 v19, v3
	v_lshl_add_u64 v[150:151], s[30:31], 0, v[4:5]
	v_mov_b32_e32 v4, v3
	v_mov_b32_e32 v5, v3
	v_mov_b32_e32 v6, v3
	v_mov_b32_e32 v7, v3
	v_mov_b32_e32 v8, v3
	v_mov_b32_e32 v9, v3
	v_mov_b32_e32 v10, v3
	v_mov_b32_e32 v11, v3
	v_mov_b32_e32 v12, v3
	v_mov_b32_e32 v13, v3
	v_mov_b32_e32 v14, v3
	v_mov_b32_e32 v15, v3
	v_mov_b32_e32 v16, v3
	v_mov_b32_e32 v17, v3
	s_waitcnt vmcnt(22)
	v_mov_b64_e32 v[34:35], v[18:19]
	s_waitcnt vmcnt(20)
	v_mov_b64_e32 v[66:67], v[18:19]
	v_mov_b64_e32 v[50:51], v[18:19]
	s_mov_b32 s39, 0
	v_ashrrev_i32_e32 v149, 31, v148
	v_mov_b32_e32 v153, 0
	s_mov_b64 s[0:1], 0
	v_mov_b64_e32 v[32:33], v[16:17]
	v_mov_b64_e32 v[30:31], v[14:15]
	v_mov_b64_e32 v[28:29], v[12:13]
	v_mov_b64_e32 v[26:27], v[10:11]
	v_mov_b64_e32 v[24:25], v[8:9]
	v_mov_b64_e32 v[22:23], v[6:7]
	v_mov_b64_e32 v[20:21], v[4:5]
	v_mov_b32_e32 v152, 0
	v_mov_b32_e32 v243, 0
	v_mov_b32_e32 v244, 0
	v_mov_b64_e32 v[64:65], v[16:17]
	v_mov_b64_e32 v[62:63], v[14:15]
	v_mov_b64_e32 v[60:61], v[12:13]
	v_mov_b64_e32 v[58:59], v[10:11]
	v_mov_b64_e32 v[56:57], v[8:9]
	v_mov_b64_e32 v[54:55], v[6:7]
	v_mov_b64_e32 v[52:53], v[4:5]
	v_mov_b64_e32 v[48:49], v[16:17]
	v_mov_b64_e32 v[46:47], v[14:15]
	v_mov_b64_e32 v[44:45], v[12:13]
	v_mov_b64_e32 v[42:43], v[10:11]
	v_mov_b64_e32 v[40:41], v[8:9]
	v_mov_b64_e32 v[38:39], v[6:7]
	v_mov_b64_e32 v[36:37], v[4:5]
	s_barrier
	s_waitcnt vmcnt(11)
	ds_write_b128 v239, v[100:103]
	s_waitcnt vmcnt(10)
	ds_write_b128 v239, v[104:107] offset:4608
	s_waitcnt vmcnt(9)
	ds_write_b128 v239, v[112:115] offset:18432
	s_waitcnt vmcnt(8)
	ds_write_b128 v239, v[128:131] offset:23040
	s_waitcnt lgkmcnt(0)
	s_barrier
	v_mov_b32_e32 v223, v219
	v_mov_b32_e32 v254, v239
	s_add_u32 s4, s0, 0x7275000
	s_addc_u32 s5, s1, 0
	s_add_u32 s6, s0, 0x72ad000
	s_addc_u32 s7, s1, 0
	v_lshl_add_u64 v[72:73], v[150:151], 0, s[4:5]
	v_lshl_add_u64 v[74:75], v[150:151], 0, s[6:7]
	global_load_dwordx4 v[100:103], v[72:73], off offset:1536
	global_load_dwordx4 v[112:115], v[72:73], off offset:2048
	global_load_dwordx4 v[104:107], v[74:75], off offset:1536
	global_load_dwordx4 v[128:131], v[74:75], off offset:2048
	v_mov_b32_e32 v224, 0
	v_mov_b32_e32 v225, 0
	v_mov_b32_e32 v226, 0
	v_mov_b32_e32 v227, 0
	v_mov_b32_e32 v228, 0
	v_mov_b32_e32 v229, 0
	v_mov_b32_e32 v230, 0
	v_mov_b32_e32 v231, 0
	v_mov_b32_e32 v232, 0
	v_mov_b32_e32 v233, 0
	v_mov_b32_e32 v234, 0
	v_mov_b32_e32 v235, 0
	v_mov_b32_e32 v236, 0
	v_mov_b32_e32 v237, 0
	v_mov_b32_e32 v238, 0
	v_mov_b32_e32 v239, 0
	v_mov_b32_e32 v244, 0
	v_mov_b32_e32 v245, 0
	v_mov_b32_e32 v246, 0
	v_mov_b32_e32 v247, 0
	v_mov_b32_e32 v248, 0
	v_mov_b32_e32 v249, 0
	v_mov_b32_e32 v250, 0
	v_mov_b32_e32 v251, 0
	v_mov_b32_e32 v243, 0
	v_lshrrev_b32_e32 v218, 4, v222
	v_xor_b32_e32 v218, v218, v222
	v_and_b32_e32 v218, 1, v218
	v_cmp_eq_u32_e32 vcc, 0, v218
	v_mov_b32_e32 v219, 0x3f803f80
	v_cndmask_b32_e32 v218, 0, v219, vcc
	v_mov_b32_e32 v219, v218
	v_mov_b32_e32 v220, v218
	v_mov_b32_e32 v221, v218
	ds_read_b128 v[186:189], v240
	ds_read_b128 v[190:193], v240 offset:32
	ds_read_b128 v[194:197], v240 offset:64
	ds_read_b128 v[198:201], v240 offset:96
	s_waitcnt vmcnt(4)
	ds_write_b128 v254, v[132:135] offset:9216
	ds_write_b128 v254, v[136:139] offset:13824
	ds_write_b128 v254, v[140:143] offset:27648
	ds_write_b128 v254, v[144:147] offset:32256
	s_waitcnt lgkmcnt(0)
	s_barrier
	s_add_u32 s4, s0, 0x72e5000
	s_addc_u32 s5, s1, 0
	s_add_u32 s6, s0, 0x731d000
	s_addc_u32 s7, s1, 0
	v_lshl_add_u64 v[72:73], v[150:151], 0, s[4:5]
	v_lshl_add_u64 v[74:75], v[150:151], 0, s[6:7]
	global_load_dwordx4 v[132:135], v[72:73], off offset:1536
	global_load_dwordx4 v[140:143], v[72:73], off offset:2048
	global_load_dwordx4 v[136:139], v[74:75], off offset:1536
	global_load_dwordx4 v[144:147], v[74:75], off offset:2048
	v_mfma_f32_32x32x16_bf16 v[68:83], v[186:189], v[120:123], v[224:239]
	v_mfma_f32_32x32x16_bf16 v[68:83], v[190:193], v[108:111], v[68:83]
	v_mfma_f32_32x32x16_bf16 v[154:169], v[194:197], v[116:119], v[224:239]
	v_mfma_f32_32x32x16_bf16 v[154:169], v[198:201], v[124:127], v[154:169]
	ds_read_b128 v[202:205], v240 offset:4608
	ds_read_b128 v[206:209], v240 offset:4640
	ds_read_b128 v[210:213], v240 offset:4672
	ds_read_b128 v[214:217], v240 offset:4704
	ds_read_b64_tr_b16 v[186:187], v241 offset:18432
	ds_read_b64_tr_b16 v[188:189], v241 offset:19584
	ds_read_b64_tr_b16 v[190:191], v241 offset:18496
	ds_read_b64_tr_b16 v[192:193], v241 offset:19648
	ds_read_b64_tr_b16 v[194:195], v241 offset:20736
	ds_read_b64_tr_b16 v[196:197], v241 offset:21888
	ds_read_b64_tr_b16 v[198:199], v241 offset:20800
	ds_read_b64_tr_b16 v[200:201], v241 offset:21952
	.p2alignl 6, 3212836864

.LBB0_1110:
	s_or_b64 exec, exec, s[0:1]
	v_readlane_b32 s0, v252, 21
	v_readlane_b32 s1, v252, 22
	v_mov_b32_e32 v4, v222
	s_andn2_b64 vcc, exec, s[0:1]
	s_waitcnt lgkmcnt(0)
	s_barrier
	s_cbranch_vccnz .LBB0_1121
	v_lshrrev_b32_e32 v0, 3, v222
	v_xor_b32_e32 v1, v0, v222
	v_and_b32_e32 v1, 7, v1
	v_lshlrev_b32_e32 v1, 4, v1
	v_lshl_add_u32 v164, v0, 7, v1
	v_add_u32_e32 v164, 32, v164
	v_and_b32_e32 v1, 7, v222
	v_lshlrev_b32_e32 v1, 4, v1
	v_lshl_or_b32 v169, v0, 11, v1
	v_add_u32_e32 v170, 0x10000, v169
	v_add_u32_e32 v171, 0x20000, v169
	v_add_u32_e32 v172, 0x30000, v169
	v_bfe_u32 v0, v222, 4, 2
	v_and_b32_e32 v1, 7, v222
	v_xor_b32_e32 v1, v0, v1
	v_lshlrev_b32_e32 v1, 4, v1
	v_and_b32_e32 v2, 15, v222
	v_xor_b32_e32 v167, 64, v1
	v_lshl_add_u32 v1, v2, 7, v1
	v_lshl_add_u32 v167, v2, 7, v167
	v_add_u32_e32 v1, 32, v1
	v_add_u32_e32 v167, 32, v167
	v_bfe_u32 v165, v222, 6, 1
	v_bfe_u32 v166, v222, 7, 1
	v_lshl_add_u32 v168, v166, 13, v167
	v_lshl_add_u32 v167, v165, 13, v167
	v_lshl_add_u32 v165, v165, 13, v1
	v_lshl_add_u32 v166, v166, 13, v1
	v_bfe_u32 v1, v222, 7, 1
	v_lshl_add_u32 v1, v1, 6, v2
	v_mul_u32_u24_e32 v1, 0x110, v1
	v_lshl_add_u32 v1, v0, 3, v1
	v_bfe_u32 v2, v222, 6, 1
	v_lshl_add_u32 v1, v2, 7, v1
	v_add_u32_e32 v173, 32, v1
	v_lshrrev_b32_e32 v0, 4, v222
	v_and_b32_e32 v1, 15, v222
	v_lshlrev_b32_e32 v1, 4, v1
	v_lshl_or_b32 v175, v0, 11, v1
	v_mul_u32_u24_e32 v0, 0x110, v0
	v_add3_u32 v174, v0, v1, 32
	v_readlane_b32 s8, v252, 19
	v_readlane_b32 s9, v252, 20
	s_lshl_b32 s0, s16, 21
	s_add_u32 s8, s8, s0
	s_addc_u32 s9, s9, 0
	v_readlane_b32 s10, v252, 3
	v_readlane_b32 s11, v252, 8
	v_readlane_b32 s13, v252, 0
	s_cmp_lt_u32 s10, 272
	s_cbranch_scc0 .Lg1_done
	s_and_b32 s12, s10, 7
	s_lshr_b32 s22, s10, 3
	s_add_i32 s22, s22, s11
	s_lshl_b32 s12, s12, 18
	s_lshl_b32 s22, s22, 18
	s_add_u32 s0, s8, s12
	s_addc_u32 s1, s9, 0
	s_add_u32 s4, s20, s22
	s_addc_u32 s5, s21, 0
	global_load_dwordx4 v[68:71], v169, s[0:1]
	global_load_dwordx4 v[84:87], v169, s[4:5]
	global_load_dwordx4 v[72:75], v170, s[0:1]
	global_load_dwordx4 v[88:91], v170, s[4:5]
	global_load_dwordx4 v[76:79], v171, s[0:1]
	global_load_dwordx4 v[92:95], v171, s[4:5]
	global_load_dwordx4 v[80:83], v172, s[0:1]
	global_load_dwordx4 v[96:99], v172, s[4:5]
	global_load_dwordx4 v[100:103], v169, s[0:1] offset:128
	global_load_dwordx4 v[116:119], v169, s[4:5] offset:128
	global_load_dwordx4 v[104:107], v170, s[0:1] offset:128
	global_load_dwordx4 v[120:123], v170, s[4:5] offset:128
	global_load_dwordx4 v[108:111], v171, s[0:1] offset:128
	global_load_dwordx4 v[124:127], v171, s[4:5] offset:128
	global_load_dwordx4 v[112:115], v172, s[0:1] offset:128
	global_load_dwordx4 v[128:131], v172, s[4:5] offset:128
	s_waitcnt vmcnt(8)
	s_branch .Lg1_pro
	.p2alignl 6, 3212836864
